# copies_to_p1_slack
# speedup vs baseline: 1.0136x; 1.0136x over previous
;     __device__ __forceinline__ bf16_t* MB() const { return (bf16_t*)(ws + WS_MB); }
;     __device__ __forceinline__ bf16_t* XB() const { return (bf16_t*)(ws + WS_XB); }
; #define CVT_REGION(src, dst, n4) do { const f32x4* s4_ = (const f32x4*)(src); unsigned long long* d8_ = (unsigned long long*)(dst); \
;         _Pragma("unroll 4") for (int i_ = gt; i_ < (n4); i_ += NT) { const f32x4 v_ = __builtin_nontemporal_load(s4_ + i_); d8_[i_] = (unsigned long long)pk2(v_.x, v_.y) | ((unsigned long long)pk2(v_.z, v_.w) << 32); } } while (0)
; __device__ __forceinline__ void xcd_barrier(const XcdBarrier& b) {
;     asm volatile("s_waitcnt vmcnt(0)" ::: "memory");
;     __syncthreads();
;     if (threadIdx.x == 0) {
;         unsigned* bar = b.bar;
;         __builtin_amdgcn_s_waitcnt(0);
;         unsigned nloc = b.st[0], nx = b.st[1];
;         if (nloc == 0u) { xcd_barrier_complete(bar, b.x, nloc, nx); b.st[0] = nloc; b.st[1] = nx; }
; __device__ __forceinline__ void p0_prologue(const Args& p, LAS unsigned char* lds, int G, int bid, int tid) {
;     ...
;     CVT_REGION(p.x_prompt(), p.XB(), NPT * (DM / 4));
;     CVT_REGION(p.x_sample(), p.XB() + (size_t)NPT * DM, NST * (DM / 4));
;     CVT_REGION(p.mem_prompt(), p.MB(), MEMROWS * (DM / 4));
.LBB0_98:
	s_or_b64 exec, exec, s[4:5]
	s_cmp_lt_i32 s89, 2
	s_cbranch_scc1 .LBB0_158
	s_waitcnt vmcnt(0)
	s_waitcnt lgkmcnt(0)
	s_barrier
	s_mov_b64 s[0:1], exec
	v_readlane_b32 s2, v242, 1
	v_readlane_b32 s3, v242, 2
	s_and_b64 s[2:3], s[0:1], s[2:3]
	s_mov_b64 exec, s[2:3]
	s_cbranch_execz .LBB0_157
	s_add_i32 s2, 0, 0x21fc0
	v_mov_b32_e32 v0, s2
	s_waitcnt vmcnt(0) expcnt(0) lgkmcnt(0)
	ds_read_b32 v2, v0
	s_add_i32 s2, 0, 0x21fc4
	v_mov_b32_e32 v0, s2
	ds_read_b32 v0, v0
	s_waitcnt lgkmcnt(1)
	v_cmp_ne_u32_e32 vcc, 0, v2
	s_cbranch_vccnz .LBB0_121
	v_readlane_b32 s2, v242, 0
	s_mul_i32 s33, s97, s2
	s_add_u32 s2, s58, 0x50200
	s_addc_u32 s3, s59, 0
	s_add_u32 s4, s58, 0x50400
	s_addc_u32 s5, s59, 0
	s_add_u32 s6, s58, 0x50500
	s_addc_u32 s7, s59, 0
	s_add_u32 s8, s58, 0x50600
	s_addc_u32 s9, s59, 0
	s_add_u32 s10, s58, 0x50700
	s_addc_u32 s11, s59, 0
	s_add_u32 s12, s58, 0x50800
	s_addc_u32 s13, s59, 0
	s_add_u32 s14, s58, 0x50900
	s_addc_u32 s15, s59, 0
	s_add_u32 s16, s58, 0x50a00
	s_addc_u32 s17, s59, 0
	s_add_u32 s18, s58, 0x50b00
	s_addc_u32 s19, s59, 0
	s_add_u32 s20, s58, 0x50c00
	s_addc_u32 s21, s59, 0
	s_add_u32 s22, s58, 0x50d00
	s_addc_u32 s23, s59, 0
	s_add_u32 s24, s58, 0x50e00
	s_addc_u32 s25, s59, 0
	s_add_u32 s26, s58, 0x50f00
	s_addc_u32 s27, s59, 0
	s_add_u32 s28, s58, 0x51000
	s_addc_u32 s29, s59, 0
	s_add_u32 s30, s58, 0x51100
	s_addc_u32 s31, s59, 0
	s_add_u32 s34, s58, 0x51200
	s_addc_u32 s35, s59, 0
	s_add_u32 s36, s58, 0x51300
	s_mul_i32 s33, s33, s96
	s_addc_u32 s37, s59, 0
	s_mov_b32 s40, 1
	v_mov_b32_e32 v16, 0
	s_branch .LBB0_109

; #define BAR_LDS() do { asm volatile("s_waitcnt lgkmcnt(0)" ::: "memory"); __builtin_amdgcn_s_barrier(); asm volatile("" ::: "memory"); } while (0)
; __device__ __forceinline__ void p0_prologue(const Args& p, LAS unsigned char* lds, int G, int bid, int tid) {
;     ...
;     for (int i = gt; i < DECB * 3328; i += NT) { const int sb = i / 3328, o = i % 3328; __builtin_nontemporal_store(__builtin_nontemporal_load((const f32x4*)(p.state_conv() + (size_t)sb * 15360 + 2048) + o), (f32x4*)(p.out() + OCS + (size_t)sb * 15360) + o); }
; template <int NC, class Epi>
; __device__ __forceinline__ void small_gemm_phase(LAS unsigned char* lds, const bf16_t* A, const bf16_t* Bt, int K, int ld, int ncolt  , const Epi& E, int first, int nblk, int bid, int tid) {
;     ...
;     BAR_LDS();
.LBB0_538:
	s_waitcnt lgkmcnt(0)
	s_barrier
	s_lshr_b32 s15, s96, 2
	s_sub_u32 s14, s96, s15
	s_sub_u32 s14, s94, s14
	v_readlane_b32 s4, v242, 29
	v_readlane_b32 s5, v242, 30
	s_nop 3
	s_add_u32 s4, s4, 0x2000
	s_addc_u32 s5, s5, 0
	s_add_u32 s6, s56, 0x5278000
	s_addc_u32 s7, s57, 0
	s_lshl_b32 s12, s14, 9
	s_lshl_b32 s8, s15, 9
	s_mov_b32 s13, 0x4ec4ec4f
	s_mov_b32 s10, 0
	s_mov_b32 s11, s14
.Lp0s_cnt_sc:
	s_cmp_ge_u32 s11, 0x340
	s_cbranch_scc1 .Lp0s_cntd_sc
	s_add_u32 s10, s10, 1
	s_add_u32 s11, s11, s15
	s_branch .Lp0s_cnt_sc

; __device__ __forceinline__ void p0_prologue(const Args& p, LAS unsigned char* lds, int G, int bid, int tid) {
;     ...
;     for (int i = gt; i < DECB * 1408; i += NT) { const int sb = i / 1408, o = i % 1408; __builtin_nontemporal_store(__builtin_nontemporal_load((const f32x4*)(p.state_pool() + (size_t)sb * 7680 + 2048) + o), (f32x4*)(p.out() + OPS + (size_t)sb * 7680) + o); }
.Lp0s_ts_sc:
	s_nop 1
	v_readlane_b32 s4, v242, 31
	v_readlane_b32 s5, v242, 32
	s_nop 3
	s_add_u32 s4, s4, 0x2000
	s_addc_u32 s5, s5, 0
	s_add_u32 s6, s56, 0x5a34000
	s_addc_u32 s7, s57, 0
	s_lshl_b32 s12, s14, 9
	s_lshl_b32 s8, s15, 9
	s_mov_b32 s13, 0x2e8ba2e9
	s_mov_b32 s10, 0
	s_mov_b32 s11, s14
.Lp0s_cnt_sp:
	s_cmp_ge_u32 s11, 0x160
	s_cbranch_scc1 .Lp0s_cntd_sp
	s_add_u32 s10, s10, 1
	s_add_u32 s11, s11, s15
	s_branch .Lp0s_cnt_sp

; __device__ __forceinline__ unsigned xb_ld(unsigned* p)              { return __hip_atomic_load(p, __ATOMIC_RELAXED, __HIP_MEMORY_SCOPE_AGENT); }
; #define SEAM(k) do { if ((k) + 1 < hi) xcd_barrier(bar); } while (0)
; __device__ __forceinline__ void xcd_barrier_complete(unsigned* bar, unsigned x, unsigned& nloc, unsigned& nx) {
;     const unsigned G = gridDim.x * gridDim.y * gridDim.z;
;     unsigned sum, cnt, mine, sp = 0u;
;     for (;;) {
;         sum = 0u; cnt = 0u; mine = 0u;
; #pragma unroll
;         for (unsigned j = 0; j < 16; ++j) { const unsigned c = xb_ld(&bar[XB_XCNT(j)]); sum += c; cnt += (c > 0u) ? 1u : 0u; mine = (j == x) ? c : mine; }
; __device__ __forceinline__ void xcd_barrier(const XcdBarrier& b) {
;     asm volatile("s_waitcnt vmcnt(0)" ::: "memory");
;     __syncthreads();
;     if (threadIdx.x == 0) {
;         unsigned* bar = b.bar;
;         __builtin_amdgcn_s_waitcnt(0);
;         unsigned nloc = b.st[0], nx = b.st[1];
;         if (nloc == 0u) { xcd_barrier_complete(bar, b.x, nloc, nx); b.st[0] = nloc; b.st[1] = nx; }
; __global__ void __launch_bounds__(512, 2) fwd_megakernel(Args a) {
;     ...
;         SEAM(1);
.Lp0s_ts_sp:
	s_nop 1
.LBB0_539:
	s_cmp_lt_i32 s89, 3
	s_cbranch_scc1 .LBB0_595
	s_waitcnt vmcnt(0)
	s_waitcnt vmcnt(0) lgkmcnt(0)
	s_barrier
	s_mov_b64 s[0:1], exec
	v_readlane_b32 s2, v242, 1
	v_readlane_b32 s3, v242, 2
	s_and_b64 s[2:3], s[0:1], s[2:3]
	s_mov_b64 exec, s[2:3]
	s_cbranch_execz .LBB0_594
	s_add_i32 s2, 0, 0x21fc0
	v_mov_b32_e32 v0, s2
	s_waitcnt vmcnt(0) expcnt(0) lgkmcnt(0)
	ds_read_b32 v2, v0
	s_add_i32 s2, 0, 0x21fc4
	v_mov_b32_e32 v0, s2
	ds_read_b32 v0, v0
	s_waitcnt lgkmcnt(1)
	v_cmp_ne_u32_e32 vcc, 0, v2
	s_cbranch_vccnz .LBB0_558
	v_readlane_b32 s2, v242, 0
	s_mul_i32 s33, s97, s2
	s_add_u32 s2, s58, 0x50200
	s_addc_u32 s3, s59, 0
	s_add_u32 s4, s58, 0x50400
	s_addc_u32 s5, s59, 0
	s_add_u32 s6, s58, 0x50500
	s_addc_u32 s7, s59, 0
	s_add_u32 s8, s58, 0x50600
	s_addc_u32 s9, s59, 0
	s_add_u32 s10, s58, 0x50700
	s_addc_u32 s11, s59, 0
	s_add_u32 s12, s58, 0x50800
	s_addc_u32 s13, s59, 0
	s_add_u32 s14, s58, 0x50900
	s_addc_u32 s15, s59, 0
	s_add_u32 s16, s58, 0x50a00
	s_addc_u32 s17, s59, 0
	s_add_u32 s18, s58, 0x50b00
	s_addc_u32 s19, s59, 0
	s_add_u32 s20, s58, 0x50c00
	s_addc_u32 s21, s59, 0
	s_add_u32 s22, s58, 0x50d00
	s_addc_u32 s23, s59, 0
	s_add_u32 s24, s58, 0x50e00
	s_addc_u32 s25, s59, 0
	s_add_u32 s26, s58, 0x50f00
	s_addc_u32 s27, s59, 0
	s_add_u32 s28, s58, 0x51000
	s_addc_u32 s29, s59, 0
	s_add_u32 s30, s58, 0x51100
	s_addc_u32 s31, s59, 0
	s_add_u32 s34, s58, 0x51200
	s_addc_u32 s35, s59, 0
	s_add_u32 s36, s58, 0x51300
	s_mul_i32 s33, s33, s96
	s_addc_u32 s37, s59, 0
	s_mov_b32 s40, 1
	v_mov_b32_e32 v16, 0
	s_branch .LBB0_544
